# v23_prio
# baseline (speedup 1.0000x reference)
; DEVI void attn_unit(const Params& p, char* lds, int au) {
;     ...
;     if (i == 1) {
;       float mm = fminf(mrun[0], mrun[1]);
; #pragma unroll
;       for (int ofs = 1; ofs < 16; ofs <<= 1) mm = fminf(mm, __shfl_xor(mm, ofs));
;       float* hx = (float*)(lds + 86016);
;       if (lane == 0) hx[wid] = qkb - mm;
;       __syncthreads();
;       const float X = fmaxf(fmaxf(fmaxf(hx[0], hx[1]), fmaxf(hx[2], hx[3])), fmaxf(fmaxf(hx[4], hx[5]), fmaxf(hx[6], hx[7]))) + 152.f;
;       float tf = X / (64.f * slope2) + 1.f;
;       const int tmax = tf > 1000.f ? 1000 : (int)tf;
;       nL = leftAvail < tmax ? leftAvail : tmax;
;       const int nR = rightAvail < tmax ? rightAvail : tmax;
;       total = 2 + nL + nR;
;     }
;     __syncthreads();
;     vcur = vnext;
.LBB0_204:
	s_or_b64 exec, exec, s[14:15]
	v_pk_add_f32 v[138:139], v[146:147], v[138:139]
	v_pk_add_f32 v[120:121], v[152:153], v[120:121]
	v_pk_add_f32 v[114:115], v[114:115], v[138:139]
	v_pk_add_f32 v[106:107], v[106:107], v[120:121]
	v_pk_add_f32 v[114:115], v[154:155], v[114:115]
	v_mov_b32_e32 v63, 0x15010
	v_pk_add_f32 v[138:139], v[148:149], v[114:115]
	v_pk_add_f32 v[114:115], v[116:117], v[118:119]
	s_waitcnt vmcnt(0) lgkmcnt(0)
	v_pk_add_f32 v[118:119], v[108:109], v[114:115]
	s_barrier
	ds_read_b128 v[114:117], v174
	v_pk_add_f32 v[96:97], v[96:97], v[106:107]
	ds_read_b128 v[106:109], v63
	v_mul_f32_e32 v0, 0x42800000, v133
	v_pk_add_f32 v[94:95], v[94:95], v[118:119]
	s_waitcnt lgkmcnt(1)
	v_max_f32_e32 v63, v115, v115
	v_max_f32_e32 v65, v114, v114
	s_waitcnt lgkmcnt(0)
	v_max_f32_e32 v109, v109, v109
	v_max_f32_e32 v108, v108, v108
	v_max_f32_e32 v63, v65, v63
	v_max_f32_e32 v65, v117, v117
	v_max_f32_e32 v114, v116, v116
	v_max_f32_e32 v108, v108, v109
	v_max_f32_e32 v65, v114, v65
	v_max3_f32 v106, v106, v107, v108
	v_max3_f32 v63, v63, v65, v106
	v_add_f32_e32 v63, 0x43180000, v63
	v_div_scale_f32 v65, s[6:7], v0, v0, v63
	v_rcp_f32_e32 v106, v65
	v_pk_add_f32 v[136:137], v[140:141], v[136:137]
	v_pk_add_f32 v[140:141], v[86:87], v[94:95]
	v_pk_add_f32 v[136:137], v[142:143], v[136:137]
	v_fma_f32 v86, -v65, v106, 1.0
	v_fmac_f32_e32 v106, v86, v106
	v_div_scale_f32 v86, vcc, v63, v0, v63
	v_mul_f32_e32 v87, v86, v106
	v_pk_add_f32 v[142:143], v[88:89], v[96:97]
	v_fma_f32 v88, -v65, v87, v86
	v_fmac_f32_e32 v87, v88, v106
	v_fma_f32 v65, -v65, v87, v86
	v_div_fmas_f32 v65, v65, v106, v87
	v_div_fixup_f32 v0, v65, v0, v63
	v_add_f32_e32 v0, 1.0, v0
	s_mov_b32 s6, 0x447a0000
	v_cmp_nle_f32_e32 vcc, s6, v0
	v_mov_b32_e32 v63, 0x447a0000
	s_and_b64 s[2:3], s[2:3], exec
	v_cndmask_b32_e32 v0, v63, v0, vcc
	v_cvt_i32_f32_e32 v0, v0
	s_cselect_b32 s2, 0x100, 32
	s_sub_i32 s2, s2, s19
	v_pk_add_f32 v[136:137], v[144:145], v[136:137]
	v_readfirstlane_b32 s3, v0
	s_min_i32 s6, s76, s3
	s_min_i32 s2, s2, s3
	s_add_i32 s2, s6, s2
	s_add_i32 s7, s2, 2
	v_pk_add_f32 v[136:137], v[150:151], v[136:137]
	s_mov_b32 s11, 2
	s_cmp_lt_i32 s7, 3
	s_barrier
	s_cbranch_scc1 .LBB0_223
	s_and_b64 vcc, exec, s[4:5]
	s_cbranch_vccnz .Lprio_skip
	s_setprio 1
.Lprio_skip:
	s_lshl_b32 s8, s18, 1
	v_add_u32_e32 v0, s19, v188
	v_mov_b32_e32 v144, v133
	v_mov_b32_e32 v145, v133
	v_mov_b32_e32 v63, v62
	v_mov_b32_e32 v86, v62
	v_mov_b32_e32 v65, v62
	v_mov_b32_e32 v87, v64
	v_mov_b32_e32 v88, v64
	v_mov_b32_e32 v89, v64
	s_sub_i32 s9, s8, s6
	s_sub_i32 s10, 0, s2
	s_mov_b32 s15, 2
	s_mov_b32 s18, 2

; DEVI void attn_unit(const Params& p, char* lds, int au) {
;     ...
;   if (typeB) PVSTEP(lds + 32768 + ((vcur == 0) ? 2 : vcur - 1) * 16384);
.LBB0_223:
	s_setprio 0
	v_mad_u64_u32 v[14:15], s[2:3], v126, s33, 0
	v_mov_b32_e32 v0, v15
	v_mad_u64_u32 v[6:7], s[2:3], v127, s33, v[0:1]
	s_lshl_b32 s6, s17, 7
	v_mov_b32_e32 v15, v6
	s_and_b64 vcc, exec, s[4:5]
	s_cbranch_vccnz .LBB0_225
	s_lshl_b32 s2, s11, 14
	s_addk_i32 s2, 0xc000
	s_cmp_lg_u32 s11, 0
	s_cselect_b32 s2, s2, 0x8000
	v_or_b32_e32 v0, s2, v185
	v_add_u32_e32 v20, v0, v183
	v_add_u32_e32 v0, v0, v184
	ds_read_b128 v[6:9], v20 offset:32768
	ds_read_b128 v[10:13], v20 offset:34816
	ds_read_b128 v[16:19], v0 offset:32768
	ds_read_b128 v[62:65], v0 offset:34816
	ds_read_b128 v[86:89], v20 offset:36864
	ds_read_b128 v[94:97], v20 offset:38912
	ds_read_b128 v[106:109], v0 offset:36864
	ds_read_b128 v[114:117], v0 offset:38912
	s_waitcnt lgkmcnt(7)
	v_mfma_f32_16x16x32_bf16 v[82:85], v[6:9], v[90:93], v[82:85]
	v_mfma_f32_16x16x32_bf16 v[6:9], v[6:9], v[110:113], v[78:81]
	s_waitcnt lgkmcnt(6)
	v_mfma_f32_16x16x32_bf16 v[74:77], v[10:13], v[90:93], v[74:77]
	v_mfma_f32_16x16x32_bf16 v[10:13], v[10:13], v[110:113], v[70:73]
	s_waitcnt lgkmcnt(3)
	v_mfma_f32_16x16x32_bf16 v[66:69], v[86:89], v[90:93], v[66:69]
	v_mfma_f32_16x16x32_bf16 v[58:61], v[86:89], v[110:113], v[58:61]
	s_waitcnt lgkmcnt(2)
	v_mfma_f32_16x16x32_bf16 v[54:57], v[94:97], v[90:93], v[54:57]
	v_mfma_f32_16x16x32_bf16 v[50:53], v[94:97], v[110:113], v[50:53]
	v_mfma_f32_16x16x32_bf16 v[82:85], v[16:19], v[98:101], v[82:85]
	v_mfma_f32_16x16x32_bf16 v[78:81], v[16:19], v[102:105], v[6:9]
	v_mfma_f32_16x16x32_bf16 v[74:77], v[62:65], v[98:101], v[74:77]
	v_mfma_f32_16x16x32_bf16 v[70:73], v[62:65], v[102:105], v[10:13]
	s_waitcnt lgkmcnt(1)
	v_mfma_f32_16x16x32_bf16 v[66:69], v[106:109], v[98:101], v[66:69]
	v_mfma_f32_16x16x32_bf16 v[58:61], v[106:109], v[102:105], v[58:61]
	s_waitcnt lgkmcnt(0)
	v_mfma_f32_16x16x32_bf16 v[54:57], v[114:117], v[98:101], v[54:57]
	v_mfma_f32_16x16x32_bf16 v[50:53], v[114:117], v[102:105], v[50:53]
	ds_read_b128 v[6:9], v20 offset:40960
	ds_read_b128 v[10:13], v20 offset:43008
	ds_read_b128 v[16:19], v0 offset:40960
	ds_read_b128 v[62:65], v0 offset:43008
	ds_read_b128 v[86:89], v20 offset:45056
	ds_read_b128 v[94:97], v20 offset:47104
	ds_read_b128 v[106:109], v0 offset:45056
	ds_read_b128 v[114:117], v0 offset:47104
	s_waitcnt lgkmcnt(7)
	v_mfma_f32_16x16x32_bf16 v[46:49], v[6:9], v[90:93], v[46:49]
	v_mfma_f32_16x16x32_bf16 v[6:9], v[6:9], v[110:113], v[42:45]
	s_waitcnt lgkmcnt(6)
	v_mfma_f32_16x16x32_bf16 v[38:41], v[10:13], v[90:93], v[38:41]
	v_mfma_f32_16x16x32_bf16 v[10:13], v[10:13], v[110:113], v[34:37]
	s_waitcnt lgkmcnt(3)
	v_mfma_f32_16x16x32_bf16 v[30:33], v[86:89], v[90:93], v[30:33]
	v_mfma_f32_16x16x32_bf16 v[26:29], v[86:89], v[110:113], v[26:29]
	s_waitcnt lgkmcnt(2)
	v_mfma_f32_16x16x32_bf16 v[20:23], v[94:97], v[90:93], v[22:25]
	v_mfma_f32_16x16x32_bf16 v[2:5], v[94:97], v[110:113], v[2:5]
	v_mfma_f32_16x16x32_bf16 v[46:49], v[16:19], v[98:101], v[46:49]
	v_mfma_f32_16x16x32_bf16 v[42:45], v[16:19], v[102:105], v[6:9]
	v_mfma_f32_16x16x32_bf16 v[38:41], v[62:65], v[98:101], v[38:41]
	v_mfma_f32_16x16x32_bf16 v[34:37], v[62:65], v[102:105], v[10:13]
	s_waitcnt lgkmcnt(1)
	v_mfma_f32_16x16x32_bf16 v[30:33], v[106:109], v[98:101], v[30:33]
	v_mfma_f32_16x16x32_bf16 v[26:29], v[106:109], v[102:105], v[26:29]
	s_waitcnt lgkmcnt(0)
	v_mfma_f32_16x16x32_bf16 v[22:25], v[114:117], v[98:101], v[20:23]
	v_mfma_f32_16x16x32_bf16 v[2:5], v[114:117], v[102:105], v[2:5]
